# P2a: tap/conversion items before the attention units, original unit order (context unit last)
# baseline (speedup 1.0000x reference)
; #define LAS __attribute__((address_space(3)))
; __device__ __forceinline__ void attn_mfma(LAS unsigned char* lds, int layer, int G, const int wave_s) {
;     ...
;     const bf16_t* Q = (const bf16_t*)(ws + WS_Q); const bf16_t* Kb = (const bf16_t*)(ws + WS_K); const bf16_t* Vb = (const bf16_t*)(ws + WS_V);
;     bf16_t* YM = (bf16_t*)(ws + WS_YM); const float* ZT = (const float*)(ws + WS_SSHY);
;     const float* gat = Pp->in[20] + layer * ATTW; const float* ghy = Pp->in[19] + layer * HY;
;     const int r32 = lane & 31, hi = lane >> 5, h = wave, kv = h >> 2;
;     const float sk = Pp->in[18][layer * NH + h] * LOG2E;
;     const unsigned lbase = (unsigned)(uintptr_t)lds;
;     LAS float* al_l = (LAS float*)(lds + AT_SCR) + wave * 64; LAS float* li_l = al_l + 32;
;     LAS float* xa = (LAS float*)(lds + AT_XA); LAS float* xh = (LAS float*)(lds + AT_XH);
;     const int nunits = layer == DEPTH - 1 ? ML / 32 : MT / 32;
;     for (int unit = blockIdx.x; unit < nunits; unit += G) {
.Lp2a_attn:
	s_cmp_lg_u32 s76, 3
	s_cselect_b64 s[44:45], -1, 0
	s_and_b64 s[0:1], s[44:45], exec
	s_movk_i32 s0, 0x110
	s_cselect_b32 s0, s0, 0x100
	s_cmp_ge_i32 s2, s0
	v_readlane_b32 s17, v253, 2
	s_mov_b64 s[36:37], s[94:95]
	v_mbcnt_lo_u32_b32 v0, -1, 0
	v_mbcnt_hi_u32_b32 v0, -1, v0
	s_cbranch_scc1 .LBB0_826
	s_load_dwordx2 s[40:41], s[36:37], 0xd8
	s_lshl_b32 s10, s76, 3
	s_lshl_b32 s1, s17, 6
	v_and_b32_e32 v184, 31, v0
	s_waitcnt vmcnt(0)
	v_lshlrev_b32_e32 v4, 4, v0
	s_waitcnt lgkmcnt(0)
	s_add_u32 s46, s40, 0xac20000
	s_addc_u32 s47, s41, 0
	s_add_u32 s48, s40, 0xb060000
	s_addc_u32 s49, s41, 0
	s_add_u32 s42, s40, 0xb4a0000
	s_addc_u32 s43, s41, 0
	s_add_i32 s10, s17, s10
	s_ashr_i32 s11, s10, 31
	s_lshl_b64 s[38:39], s[10:11], 2
	s_load_dwordx2 s[10:11], s[36:37], 0x90
	s_load_dwordx4 s[52:55], s[36:37], 0x98
	v_and_b32_e32 v6, 0xc0, v4
	v_lshlrev_b32_e32 v7, 1, v0
	v_and_b32_e32 v7, 32, v7
	s_waitcnt lgkmcnt(0)
	s_add_u32 s10, s10, s38
	s_addc_u32 s11, s11, s39
	global_load_dword v2, v1, s[10:11]
	s_lshl_b32 s10, s17, 8
	s_add_i32 s15, s10, 0
	s_lshl_b32 s26, s76, 10
	s_add_i32 s15, s15, 0x20000
	s_lshl_b64 s[10:11], s[26:27], 2
	s_add_u32 s56, s52, s10
	s_addc_u32 s57, s53, s11
	s_add_u32 s54, s54, s10
	s_addc_u32 s55, s55, s11
	s_lshl_b32 s60, s17, 7
	s_ashr_i32 s61, s60, 31
	s_lshl_b64 s[52:53], s[60:61], 1
	s_add_u32 s10, s40, s52
	s_addc_u32 s11, s41, s53
	s_add_u32 s50, s10, 0x9b20000
	s_addc_u32 s51, s11, 0
	s_lshl_b32 s10, s17, 12
	s_and_b32 s10, s10, 0xffffc000
	s_add_i32 s11, s10, 0
	v_lshl_add_u32 v188, v184, 8, s11
	s_add_i32 s11, 0, 0x8000
	v_add_u32_e32 v6, s11, v6
	v_ashrrev_i32_e32 v185, 5, v0
	v_mov_b32_e32 v163, v1
	s_mulk_i32 s17, 0x2200
	v_lshlrev_b32_e32 v187, 4, v185
	v_cmp_gt_u32_e64 s[36:37], 32, v0
	s_mov_b64 s[28:29], 0xd6a0000
	s_add_i32 s17, s17, 0
	v_ashrrev_i32_e32 v194, 4, v0
	v_lshl_add_u32 v193, v184, 1, s17
	v_lshlrev_b32_e32 v189, 2, v185
	v_lshlrev_b32_e32 v5, 2, v184
	v_readlane_b32 s23, v255, 7
	s_add_i32 s11, s60, 0
	s_add_i32 s11, s11, 0x20c00
	v_add_u32_e32 v190, s15, v5
	v_add_u32_e32 v209, s15, v187
	s_movk_i32 s15, 0x440
	v_cmp_eq_u32_e64 s[38:39], 0, v184
	s_waitcnt vmcnt(0)
	v_mul_f32_e32 v186, 0x3fb8aa3b, v2
	v_lshlrev_b32_e32 v2, 3, v0
	v_and_b32_e32 v3, 24, v2
	v_and_b32_e32 v2, 0x100, v2
	v_add3_u32 v3, v6, v3, v7
	v_add3_u32 v191, v3, v2, s10
	v_and_b32_e32 v2, 7, v0
	v_lshlrev_b32_e32 v162, 4, v2
	v_and_b32_e32 v6, -8, v0
	v_lshlrev_b32_e32 v192, 2, v2
	v_lshl_add_u64 v[2:3], s[40:41], 0, v[162:163]
	v_cmp_gt_i32_e64 s[40:41], 8, v0
	v_and_b32_e32 v0, 0xf0, v4
	v_lshl_add_u64 v[164:165], v[2:3], 0, s[28:29]
	v_add_u32_e32 v196, s17, v0
	s_movk_i32 s17, 0x70
	v_add_u32_e32 v3, 32, v187
	v_bitop3_b32 v202, v3, v4, s17 bitop3:0x78
	v_add_u32_e32 v3, 64, v187
	v_bitop3_b32 v203, v3, v4, s17 bitop3:0x78
	v_add_u32_e32 v3, 0x60, v187
	v_bitop3_b32 v204, v3, v4, s17 bitop3:0x78
	v_add_u32_e32 v3, 0x80, v187
	v_bitop3_b32 v205, v3, v4, s17 bitop3:0x78
	v_add_u32_e32 v3, 0xa0, v187
	v_bitop3_b32 v206, v3, v4, s17 bitop3:0x78
	v_add_u32_e32 v3, 0xc0, v187
	v_bitop3_b32 v207, v3, v4, s17 bitop3:0x78
	v_add_u32_e32 v3, 0xe0, v187
	v_or_b32_e32 v2, s60, v184
	v_bitop3_b32 v200, v187, v4, s17 bitop3:0x78
	v_bitop3_b32 v208, v3, v4, s17 bitop3:0x78
	v_add_u32_e32 v4, s1, v6
	s_mov_b32 s17, 0x8800
	v_add_u32_e32 v6, 0x200, v4
	v_ashrrev_i32_e32 v3, 31, v2
	s_add_i32 s10, s23, s60
	v_add_u32_e32 v163, s23, v5
	s_movk_i32 s23, 0x110
	v_mad_i64_i32 v[166:167], s[28:29], v4, s17, 0
	v_mad_i64_i32 v[168:169], s[28:29], v6, s17, 0
	v_lshl_add_u64 v[180:181], v[2:3], 2, s[54:55]
	v_or_b32_e32 v3, 1, v189
	v_mul_lo_u32 v198, v194, s23
	v_ashrrev_i32_e32 v5, 31, v4
	v_mul_lo_u32 v210, v3, s23
	s_add_u32 s28, s42, s52
	v_ashrrev_i32_e32 v7, 31, v6
	v_lshl_add_u64 v[174:175], v[4:5], 2, s[56:57]
	v_lshl_add_u64 v[176:177], v[4:5], 1, s[42:43]
	v_mul_lo_u32 v2, v185, s15
	v_add_u32_e32 v3, 0x990, v210
	v_add_u32_e32 v4, 0x440, v198
	s_addc_u32 s29, s43, s53
	v_lshl_add_u64 v[178:179], v[6:7], 1, s[42:43]
	v_lshl_add_u64 v[182:183], s[28:29], 0, v[0:1]
	v_add_u32_e32 v211, v193, v2
	v_add_u32_e32 v212, v193, v3
	v_add_u32_e32 v213, v196, v4
	v_mbcnt_lo_u32_b32 v66, -1, 0
	v_mbcnt_hi_u32_b32 v66, -1, v66
	v_add_u32_e32 v67, s1, v66
	v_ashrrev_i32_e32 v68, 4, v67
	v_and_b32_e32 v70, 0xfffff0, v68
	v_lshlrev_b32_e32 v71, 1, v68
	v_lshlrev_b32_e32 v66, 3, v66
	v_and_or_b32 v70, v71, 8, v70
	v_and_b32_e32 v69, 0x78, v66
	v_lshrrev_b32_e32 v70, 1, v70
	v_bfe_u32 v66, v66, 5, 2
	v_lshrrev_b32_e32 v71, 1, v68
	v_or_b32_e32 v66, v70, v66
	v_and_b32_e32 v70, 3, v68
	v_lshlrev_b32_e32 v69, 1, v69
	v_and_or_b32 v70, v71, 4, v70
	v_and_b32_e32 v71, 48, v69
	v_lshlrev_b32_e32 v68, 8, v68
	v_and_b32_e32 v67, 0x70, v67
	v_lshl_or_b32 v70, v70, 6, v71
	v_bitop3_b32 v67, v69, v68, v67 bitop3:0xde
	v_lshl_or_b32 v66, v66, 9, v70
	v_mov_b32_e32 v233, v67
	v_mov_b32_e32 v234, v66
	v_mbcnt_lo_u32_b32 v236, -1, 0
	v_mbcnt_hi_u32_b32 v236, -1, v236
	v_add_u32_e32 v235, s1, v236
	v_ashrrev_i32_e32 v235, 4, v235
	v_lshlrev_b32_e32 v236, 4, v236
	v_and_b32_e32 v236, 0xf0, v236
	s_mov_b32 s15, s2
	s_branch .LBB0_789
